# v75 stack + sc1 (write-through) on the P1 XN/XN8 stores: less dirty L2 at the seam, still allocated in the memory-side cache
# speedup vs baseline: 1.0046x; 1.0046x over previous
.Lp1_a_go:
	s_mov_b32 s26, 0
	s_lshl_b32 s0, s4, 11
	s_add_u32 s16, s10, s0
	s_addc_u32 s17, s11, 0
	s_lshl_b32 s0, s4, 10
	s_add_u32 s18, s14, s0
	s_addc_u32 s19, s15, 0
	v_pk_mul_f32 v[54:55], v[4:5], v[4:5]
	v_pk_mul_f32 v[56:57], v[6:7], v[6:7]
	v_pk_fma_f32 v[54:55], v[8:9], v[8:9], v[54:55]
	v_pk_fma_f32 v[56:57], v[10:11], v[10:11], v[56:57]
	v_pk_fma_f32 v[54:55], v[12:13], v[12:13], v[54:55]
	v_pk_fma_f32 v[56:57], v[14:15], v[14:15], v[56:57]
	v_pk_fma_f32 v[54:55], v[16:17], v[16:17], v[54:55]
	v_pk_fma_f32 v[56:57], v[18:19], v[18:19], v[56:57]
	v_pk_add_f32 v[54:55], v[54:55], v[56:57]
	s_nop 0
	v_add_f32_e32 v52, v54, v55
	s_nop 1
	v_add_f32_dpp v52, v52, v52 quad_perm:[1,0,3,2] row_mask:0xf bank_mask:0xf
	s_nop 1
	v_add_f32_dpp v52, v52, v52 quad_perm:[2,3,0,1] row_mask:0xf bank_mask:0xf
	s_nop 1
	v_add_f32_dpp v52, v52, v52 row_half_mirror row_mask:0xf bank_mask:0xf
	s_nop 1
	v_add_f32_dpp v52, v52, v52 row_mirror row_mask:0xf bank_mask:0xf
	s_nop 1
	v_add_f32_dpp v52, v52, v52 row_bcast:15 row_mask:0xa bank_mask:0xf
	s_nop 1
	v_add_f32_dpp v52, v52, v52 row_bcast:31 row_mask:0xc bank_mask:0xf
	s_nop 1
	v_readlane_b32 s27, v52, 63
	s_nop 3
	v_mov_b32_e32 v52, s27
	v_fmamk_f32 v52, v52, 0x3a800000, v204
	v_rsq_f32_e32 v52, v52
	s_nop 1
	v_pk_mul_f32 v[4:5], v[4:5], v[52:53] op_sel_hi:[1,0]
	v_pk_mul_f32 v[6:7], v[6:7], v[52:53] op_sel_hi:[1,0]
	v_pk_mul_f32 v[8:9], v[8:9], v[52:53] op_sel_hi:[1,0]
	v_pk_mul_f32 v[10:11], v[10:11], v[52:53] op_sel_hi:[1,0]
	v_pk_mul_f32 v[12:13], v[12:13], v[52:53] op_sel_hi:[1,0]
	v_pk_mul_f32 v[14:15], v[14:15], v[52:53] op_sel_hi:[1,0]
	v_pk_mul_f32 v[16:17], v[16:17], v[52:53] op_sel_hi:[1,0]
	v_pk_mul_f32 v[18:19], v[18:19], v[52:53] op_sel_hi:[1,0]
	v_pk_mul_f32 v[4:5], v[172:173], v[4:5]
	v_pk_mul_f32 v[6:7], v[174:175], v[6:7]
	v_pk_mul_f32 v[8:9], v[176:177], v[8:9]
	v_pk_mul_f32 v[10:11], v[178:179], v[10:11]
	v_pk_mul_f32 v[12:13], v[180:181], v[12:13]
	v_pk_mul_f32 v[14:15], v[182:183], v[14:15]
	v_pk_mul_f32 v[16:17], v[184:185], v[16:17]
	v_pk_mul_f32 v[18:19], v[186:187], v[18:19]
	v_pk_add_f32 v[20:21], v[20:21], 1.0 op_sel_hi:[1,0]
	v_pk_add_f32 v[22:23], v[22:23], 1.0 op_sel_hi:[1,0]
	v_pk_add_f32 v[24:25], v[24:25], 1.0 op_sel_hi:[1,0]
	v_pk_add_f32 v[26:27], v[26:27], 1.0 op_sel_hi:[1,0]
	v_pk_add_f32 v[28:29], v[28:29], 1.0 op_sel_hi:[1,0]
	v_pk_add_f32 v[30:31], v[30:31], 1.0 op_sel_hi:[1,0]
	v_pk_add_f32 v[32:33], v[32:33], 1.0 op_sel_hi:[1,0]
	v_pk_add_f32 v[34:35], v[34:35], 1.0 op_sel_hi:[1,0]
	v_pk_fma_f32 v[4:5], v[20:21], v[4:5], v[36:37]
	v_pk_fma_f32 v[6:7], v[22:23], v[6:7], v[38:39]
	v_pk_fma_f32 v[8:9], v[24:25], v[8:9], v[40:41]
	v_pk_fma_f32 v[10:11], v[26:27], v[10:11], v[42:43]
	v_pk_fma_f32 v[12:13], v[28:29], v[12:13], v[44:45]
	v_pk_fma_f32 v[14:15], v[30:31], v[14:15], v[46:47]
	v_pk_fma_f32 v[16:17], v[32:33], v[16:17], v[48:49]
	v_pk_fma_f32 v[18:19], v[34:35], v[18:19], v[50:51]
	v_cvt_pk_bf16_f32 v206, v4, v5
	v_cvt_pk_bf16_f32 v207, v6, v7
	v_cvt_pk_fp8_f32 v214, v4, v5
	v_cvt_pk_bf16_f32 v208, v8, v9
	v_cvt_pk_bf16_f32 v209, v10, v11
	v_cvt_pk_fp8_f32 v215, v8, v9
	v_cvt_pk_bf16_f32 v210, v12, v13
	v_cvt_pk_bf16_f32 v211, v14, v15
	v_cvt_pk_fp8_f32 v216, v12, v13
	v_cvt_pk_bf16_f32 v212, v16, v17
	v_cvt_pk_bf16_f32 v213, v18, v19
	v_cvt_pk_fp8_f32 v217, v16, v17
	v_cvt_pk_fp8_f32 v214, v6, v7 op_sel:[0,0,1]
	v_cvt_pk_fp8_f32 v215, v10, v11 op_sel:[0,0,1]
	v_cvt_pk_fp8_f32 v216, v14, v15 op_sel:[0,0,1]
	v_cvt_pk_fp8_f32 v217, v18, v19 op_sel:[0,0,1]
	s_nop 1
	global_store_dwordx2 v2, v[206:207], s[16:17] sc1
	global_store_dwordx2 v2, v[208:209], s[16:17] offset:512 sc1
	global_store_dwordx2 v2, v[210:211], s[16:17] offset:1024 sc1
	global_store_dwordx2 v2, v[212:213], s[16:17] offset:1536 sc1
	global_store_dword v3, v214, s[18:19] sc1
	global_store_dword v3, v215, s[18:19] offset:256 sc1
	global_store_dword v3, v216, s[18:19] offset:512 sc1
	global_store_dword v3, v217, s[18:19] offset:768 sc1
	s_cmp_gt_i32 s5, 0x83ff
	s_cbranch_scc1 .Lp1_done
	s_mov_b32 s4, s5

.Lp1_b_go:
	s_mov_b32 s26, 0
	s_lshl_b32 s0, s4, 11
	s_add_u32 s16, s10, s0
	s_addc_u32 s17, s11, 0
	s_lshl_b32 s0, s4, 10
	s_add_u32 s18, s14, s0
	s_addc_u32 s19, s15, 0
	v_pk_mul_f32 v[54:55], v[188:189], v[188:189]
	v_pk_mul_f32 v[56:57], v[190:191], v[190:191]
	v_pk_fma_f32 v[54:55], v[192:193], v[192:193], v[54:55]
	v_pk_fma_f32 v[56:57], v[194:195], v[194:195], v[56:57]
	v_pk_fma_f32 v[54:55], v[196:197], v[196:197], v[54:55]
	v_pk_fma_f32 v[56:57], v[198:199], v[198:199], v[56:57]
	v_pk_fma_f32 v[54:55], v[200:201], v[200:201], v[54:55]
	v_pk_fma_f32 v[56:57], v[202:203], v[202:203], v[56:57]
	v_pk_add_f32 v[54:55], v[54:55], v[56:57]
	s_nop 0
	v_add_f32_e32 v52, v54, v55
	s_nop 1
	v_add_f32_dpp v52, v52, v52 quad_perm:[1,0,3,2] row_mask:0xf bank_mask:0xf
	s_nop 1
	v_add_f32_dpp v52, v52, v52 quad_perm:[2,3,0,1] row_mask:0xf bank_mask:0xf
	s_nop 1
	v_add_f32_dpp v52, v52, v52 row_half_mirror row_mask:0xf bank_mask:0xf
	s_nop 1
	v_add_f32_dpp v52, v52, v52 row_mirror row_mask:0xf bank_mask:0xf
	s_nop 1
	v_add_f32_dpp v52, v52, v52 row_bcast:15 row_mask:0xa bank_mask:0xf
	s_nop 1
	v_add_f32_dpp v52, v52, v52 row_bcast:31 row_mask:0xc bank_mask:0xf
	s_nop 1
	v_readlane_b32 s27, v52, 63
	s_nop 3
	v_mov_b32_e32 v52, s27
	v_fmamk_f32 v52, v52, 0x3a800000, v204
	v_rsq_f32_e32 v52, v52
	s_nop 1
	v_pk_mul_f32 v[188:189], v[188:189], v[52:53] op_sel_hi:[1,0]
	v_pk_mul_f32 v[190:191], v[190:191], v[52:53] op_sel_hi:[1,0]
	v_pk_mul_f32 v[192:193], v[192:193], v[52:53] op_sel_hi:[1,0]
	v_pk_mul_f32 v[194:195], v[194:195], v[52:53] op_sel_hi:[1,0]
	v_pk_mul_f32 v[196:197], v[196:197], v[52:53] op_sel_hi:[1,0]
	v_pk_mul_f32 v[198:199], v[198:199], v[52:53] op_sel_hi:[1,0]
	v_pk_mul_f32 v[200:201], v[200:201], v[52:53] op_sel_hi:[1,0]
	v_pk_mul_f32 v[202:203], v[202:203], v[52:53] op_sel_hi:[1,0]
	v_pk_mul_f32 v[188:189], v[172:173], v[188:189]
	v_pk_mul_f32 v[190:191], v[174:175], v[190:191]
	v_pk_mul_f32 v[192:193], v[176:177], v[192:193]
	v_pk_mul_f32 v[194:195], v[178:179], v[194:195]
	v_pk_mul_f32 v[196:197], v[180:181], v[196:197]
	v_pk_mul_f32 v[198:199], v[182:183], v[198:199]
	v_pk_mul_f32 v[200:201], v[184:185], v[200:201]
	v_pk_mul_f32 v[202:203], v[186:187], v[202:203]
	v_pk_add_f32 v[220:221], v[220:221], 1.0 op_sel_hi:[1,0]
	v_pk_add_f32 v[222:223], v[222:223], 1.0 op_sel_hi:[1,0]
	v_pk_add_f32 v[224:225], v[224:225], 1.0 op_sel_hi:[1,0]
	v_pk_add_f32 v[226:227], v[226:227], 1.0 op_sel_hi:[1,0]
	v_pk_add_f32 v[228:229], v[228:229], 1.0 op_sel_hi:[1,0]
	v_pk_add_f32 v[230:231], v[230:231], 1.0 op_sel_hi:[1,0]
	v_pk_add_f32 v[232:233], v[232:233], 1.0 op_sel_hi:[1,0]
	v_pk_add_f32 v[234:235], v[234:235], 1.0 op_sel_hi:[1,0]
	v_pk_fma_f32 v[188:189], v[220:221], v[188:189], v[236:237]
	v_pk_fma_f32 v[190:191], v[222:223], v[190:191], v[238:239]
	v_pk_fma_f32 v[192:193], v[224:225], v[192:193], v[240:241]
	v_pk_fma_f32 v[194:195], v[226:227], v[194:195], v[242:243]
	v_pk_fma_f32 v[196:197], v[228:229], v[196:197], v[244:245]
	v_pk_fma_f32 v[198:199], v[230:231], v[198:199], v[246:247]
	v_pk_fma_f32 v[200:201], v[232:233], v[200:201], v[248:249]
	v_pk_fma_f32 v[202:203], v[234:235], v[202:203], v[250:251]
	v_cvt_pk_bf16_f32 v206, v188, v189
	v_cvt_pk_bf16_f32 v207, v190, v191
	v_cvt_pk_fp8_f32 v214, v188, v189
	v_cvt_pk_bf16_f32 v208, v192, v193
	v_cvt_pk_bf16_f32 v209, v194, v195
	v_cvt_pk_fp8_f32 v215, v192, v193
	v_cvt_pk_bf16_f32 v210, v196, v197
	v_cvt_pk_bf16_f32 v211, v198, v199
	v_cvt_pk_fp8_f32 v216, v196, v197
	v_cvt_pk_bf16_f32 v212, v200, v201
	v_cvt_pk_bf16_f32 v213, v202, v203
	v_cvt_pk_fp8_f32 v217, v200, v201
	v_cvt_pk_fp8_f32 v214, v190, v191 op_sel:[0,0,1]
	v_cvt_pk_fp8_f32 v215, v194, v195 op_sel:[0,0,1]
	v_cvt_pk_fp8_f32 v216, v198, v199 op_sel:[0,0,1]
	v_cvt_pk_fp8_f32 v217, v202, v203 op_sel:[0,0,1]
	s_nop 1
	global_store_dwordx2 v2, v[206:207], s[16:17] sc1
	global_store_dwordx2 v2, v[208:209], s[16:17] offset:512 sc1
	global_store_dwordx2 v2, v[210:211], s[16:17] offset:1024 sc1
	global_store_dwordx2 v2, v[212:213], s[16:17] offset:1536 sc1
	global_store_dword v3, v214, s[18:19] sc1
	global_store_dword v3, v215, s[18:19] offset:256 sc1
	global_store_dword v3, v216, s[18:19] offset:512 sc1
	global_store_dword v3, v217, s[18:19] offset:768 sc1
	s_cmp_gt_i32 s5, 0x83ff
	s_cbranch_scc1 .Lp1_done
	s_mov_b32 s4, s5
	s_branch .Lp1_a
